# diff-lat attention inner block software-pipelined by hand (QK of next unit and PV of previous unit overlap softmax VALU)
# speedup vs baseline: 1.1653x; 1.0031x over previous
.LBB0_727:
	v_add_u32_e32 v250, 0x2000, v163
	ds_read2_b64 v[142:145], v163 offset0:0 offset1:2
	ds_read2_b64 v[138:141], v163 offset0:4 offset1:6
	ds_read2_b64 v[134:137], v250 offset0:32 offset1:34
	ds_read2_b64 v[130:133], v250 offset0:36 offset1:38
	ds_read_b128 v[242:245], v161 offset:0
	ds_read_b128 v[246:249], v161 offset:32
	s_waitcnt lgkmcnt(0)
	v_mfma_f32_32x32x16_bf16 v[66:81], v[242:245], v[82:85], 0
	v_mfma_f32_32x32x16_bf16 v[66:81], v[246:249], v[86:89], v[66:81]
	s_nop 15
	v_max3_f32 v185, v66, v67, v68
	v_max3_f32 v185, v185, v69, v70
	v_max3_f32 v185, v185, v71, v72
	v_max3_f32 v185, v185, v73, v74
	v_max3_f32 v185, v185, v75, v76
	ds_read_b128 v[242:245], v161 offset:64
	ds_read_b128 v[246:249], v161 offset:96
	v_max3_f32 v185, v185, v77, v78
	v_max3_f32 v185, v185, v79, v80
	v_max_f32_e32 v185, v185, v81
	v_mov_b32_e32 v188, v185
	s_nop 1
	v_permlane32_swap_b32_e32 v185, v188
	v_max_f32_e32 v185, v185, v188
	v_fma_f32 v188, v185, s75, -v224
	v_cmp_lt_f32_e32 vcc, s73, v188
	s_cbranch_vccz .Lda_dl_nr0
	v_mul_f32_e32 v185, 0x3e8293ee, v185
	v_max_f32_e32 v185, v224, v185
	v_sub_f32_e32 v188, v224, v185
	v_exp_f32_e32 v188, v188
	v_mov_b32_e32 v224, v185
	s_nop 0
	v_mul_f32_e32 v157, v157, v188
	v_pk_mul_f32 v[50:51], v[50:51], v[188:189] op_sel_hi:[1,0]
	v_pk_mul_f32 v[52:53], v[52:53], v[188:189] op_sel_hi:[1,0]
	v_pk_mul_f32 v[54:55], v[54:55], v[188:189] op_sel_hi:[1,0]
	v_pk_mul_f32 v[56:57], v[56:57], v[188:189] op_sel_hi:[1,0]
	v_pk_mul_f32 v[58:59], v[58:59], v[188:189] op_sel_hi:[1,0]
	v_pk_mul_f32 v[60:61], v[60:61], v[188:189] op_sel_hi:[1,0]
	v_pk_mul_f32 v[62:63], v[62:63], v[188:189] op_sel_hi:[1,0]
	v_pk_mul_f32 v[64:65], v[64:65], v[188:189] op_sel_hi:[1,0]
	v_pk_mul_f32 v[18:19], v[18:19], v[188:189] op_sel_hi:[1,0]
	v_pk_mul_f32 v[20:21], v[20:21], v[188:189] op_sel_hi:[1,0]
	v_pk_mul_f32 v[22:23], v[22:23], v[188:189] op_sel_hi:[1,0]
	v_pk_mul_f32 v[24:25], v[24:25], v[188:189] op_sel_hi:[1,0]
	v_pk_mul_f32 v[26:27], v[26:27], v[188:189] op_sel_hi:[1,0]
	v_pk_mul_f32 v[28:29], v[28:29], v[188:189] op_sel_hi:[1,0]
	v_pk_mul_f32 v[30:31], v[30:31], v[188:189] op_sel_hi:[1,0]
	v_pk_mul_f32 v[32:33], v[32:33], v[188:189] op_sel_hi:[1,0]
.Lda_dl_nr0:
	v_fma_f32 v66, v66, s75, -v224
	v_exp_f32_e32 v66, v66
	v_fma_f32 v67, v67, s75, -v224
	v_exp_f32_e32 v67, v67
	v_mov_b32_e32 v193, v66
	v_fma_f32 v68, v68, s75, -v224
	v_exp_f32_e32 v68, v68
	v_mov_b32_e32 v194, v67
	v_fma_f32 v69, v69, s75, -v224
	v_exp_f32_e32 v69, v69
	v_add_f32_e32 v193, v68, v193
	v_fma_f32 v70, v70, s75, -v224
	s_waitcnt lgkmcnt(0)
	v_mfma_f32_32x32x16_bf16 v[226:241], v[242:245], v[90:93], 0
	v_exp_f32_e32 v70, v70
	v_add_f32_e32 v194, v69, v194
	v_fma_f32 v71, v71, s75, -v224
	v_exp_f32_e32 v71, v71
	v_add_f32_e32 v193, v70, v193
	v_fma_f32 v72, v72, s75, -v224
	v_exp_f32_e32 v72, v72
	v_add_f32_e32 v194, v71, v194
	v_fma_f32 v73, v73, s75, -v224
	v_exp_f32_e32 v73, v73
	v_add_f32_e32 v193, v72, v193
	v_fma_f32 v74, v74, s75, -v224
	v_exp_f32_e32 v74, v74
	v_add_f32_e32 v194, v73, v194
	v_fma_f32 v75, v75, s75, -v224
	v_exp_f32_e32 v75, v75
	v_add_f32_e32 v193, v74, v193
	v_fma_f32 v76, v76, s75, -v224
	v_mfma_f32_32x32x16_bf16 v[226:241], v[246:249], v[94:97], v[226:241]
	v_exp_f32_e32 v76, v76
	v_add_f32_e32 v194, v75, v194
	v_fma_f32 v77, v77, s75, -v224
	v_exp_f32_e32 v77, v77
	v_add_f32_e32 v193, v76, v193
	v_fma_f32 v78, v78, s75, -v224
	v_exp_f32_e32 v78, v78
	v_add_f32_e32 v194, v77, v194
	v_fma_f32 v79, v79, s75, -v224
	v_exp_f32_e32 v79, v79
	v_add_f32_e32 v193, v78, v193
	v_fma_f32 v80, v80, s75, -v224
	v_exp_f32_e32 v80, v80
	v_add_f32_e32 v194, v79, v194
	v_fma_f32 v81, v81, s75, -v224
	v_exp_f32_e32 v81, v81
	v_add_f32_e32 v193, v80, v193
	v_add_f32_e32 v194, v81, v194
	v_add_f32_e32 v193, v193, v194
	v_cvt_pk_bf16_f32 v242, v66, v67
	v_cvt_pk_bf16_f32 v243, v68, v69
	v_cvt_pk_bf16_f32 v244, v70, v71
	v_cvt_pk_bf16_f32 v245, v72, v73
	v_cvt_pk_bf16_f32 v246, v74, v75
	v_cvt_pk_bf16_f32 v247, v76, v77
	v_cvt_pk_bf16_f32 v248, v78, v79
	v_cvt_pk_bf16_f32 v249, v80, v81
	v_add_f32_e32 v157, v157, v193
	s_waitcnt lgkmcnt(0)
	s_nop 1
	v_mfma_f32_32x32x16_bf16 v[50:65], v[142:145], v[242:245], v[50:65]
	v_max3_f32 v185, v226, v227, v228
	v_mfma_f32_32x32x16_bf16 v[18:33], v[134:137], v[242:245], v[18:33]
	ds_read_b128 v[242:245], v161 offset:4608
	v_max3_f32 v185, v185, v229, v230
	v_max3_f32 v185, v185, v231, v232
	v_mfma_f32_32x32x16_bf16 v[50:65], v[138:141], v[246:249], v[50:65]
	v_max3_f32 v185, v185, v233, v234
	v_max3_f32 v185, v185, v235, v236
	v_mfma_f32_32x32x16_bf16 v[18:33], v[130:133], v[246:249], v[18:33]
	ds_read_b128 v[246:249], v161 offset:4640
	v_max3_f32 v185, v185, v237, v238
	v_max3_f32 v185, v185, v239, v240
	v_max_f32_e32 v185, v185, v241
	v_mov_b32_e32 v188, v185
	s_nop 1
	v_permlane32_swap_b32_e32 v185, v188
	v_max_f32_e32 v185, v185, v188
	v_fma_f32 v188, v185, s75, -v223
	v_cmp_lt_f32_e32 vcc, s73, v188
	s_cbranch_vccz .Lda_dl_nr1
	v_mul_f32_e32 v185, 0x3e8293ee, v185
	v_max_f32_e32 v185, v223, v185
	v_sub_f32_e32 v188, v223, v185
	v_exp_f32_e32 v188, v188
	v_mov_b32_e32 v223, v185
	s_nop 0
	v_mul_f32_e32 v155, v155, v188
	v_pk_mul_f32 v[34:35], v[34:35], v[188:189] op_sel_hi:[1,0]
	v_pk_mul_f32 v[36:37], v[36:37], v[188:189] op_sel_hi:[1,0]
	v_pk_mul_f32 v[38:39], v[38:39], v[188:189] op_sel_hi:[1,0]
	v_pk_mul_f32 v[40:41], v[40:41], v[188:189] op_sel_hi:[1,0]
	v_pk_mul_f32 v[42:43], v[42:43], v[188:189] op_sel_hi:[1,0]
	v_pk_mul_f32 v[44:45], v[44:45], v[188:189] op_sel_hi:[1,0]
	v_pk_mul_f32 v[46:47], v[46:47], v[188:189] op_sel_hi:[1,0]
	v_pk_mul_f32 v[48:49], v[48:49], v[188:189] op_sel_hi:[1,0]
	v_pk_mul_f32 v[2:3], v[2:3], v[188:189] op_sel_hi:[1,0]
	v_pk_mul_f32 v[4:5], v[4:5], v[188:189] op_sel_hi:[1,0]
	v_pk_mul_f32 v[6:7], v[6:7], v[188:189] op_sel_hi:[1,0]
	v_pk_mul_f32 v[8:9], v[8:9], v[188:189] op_sel_hi:[1,0]
	v_pk_mul_f32 v[10:11], v[10:11], v[188:189] op_sel_hi:[1,0]
	v_pk_mul_f32 v[12:13], v[12:13], v[188:189] op_sel_hi:[1,0]
	v_pk_mul_f32 v[14:15], v[14:15], v[188:189] op_sel_hi:[1,0]
	v_pk_mul_f32 v[16:17], v[16:17], v[188:189] op_sel_hi:[1,0]
.Lda_dl_nr1:
	v_fma_f32 v226, v226, s75, -v223
	v_exp_f32_e32 v226, v226
	v_fma_f32 v227, v227, s75, -v223
	v_exp_f32_e32 v227, v227
	v_mov_b32_e32 v193, v226
	v_fma_f32 v228, v228, s75, -v223
	v_exp_f32_e32 v228, v228
	v_mov_b32_e32 v194, v227
	v_fma_f32 v229, v229, s75, -v223
	v_exp_f32_e32 v229, v229
	v_add_f32_e32 v193, v228, v193
	v_fma_f32 v230, v230, s75, -v223
	s_waitcnt lgkmcnt(0)
	v_mfma_f32_32x32x16_bf16 v[66:81], v[242:245], v[82:85], 0
	v_exp_f32_e32 v230, v230
	v_add_f32_e32 v194, v229, v194
	v_fma_f32 v231, v231, s75, -v223
	v_exp_f32_e32 v231, v231
	v_add_f32_e32 v193, v230, v193
	v_fma_f32 v232, v232, s75, -v223
	v_exp_f32_e32 v232, v232
	v_add_f32_e32 v194, v231, v194
	v_fma_f32 v233, v233, s75, -v223
	v_exp_f32_e32 v233, v233
	v_add_f32_e32 v193, v232, v193
	v_fma_f32 v234, v234, s75, -v223
	v_exp_f32_e32 v234, v234
	v_add_f32_e32 v194, v233, v194
	v_fma_f32 v235, v235, s75, -v223
	v_exp_f32_e32 v235, v235
	v_add_f32_e32 v193, v234, v193
	v_fma_f32 v236, v236, s75, -v223
	v_mfma_f32_32x32x16_bf16 v[66:81], v[246:249], v[86:89], v[66:81]
	v_exp_f32_e32 v236, v236
	v_add_f32_e32 v194, v235, v194
	v_fma_f32 v237, v237, s75, -v223
	v_exp_f32_e32 v237, v237
	v_add_f32_e32 v193, v236, v193
	v_fma_f32 v238, v238, s75, -v223
	v_exp_f32_e32 v238, v238
	v_add_f32_e32 v194, v237, v194
	v_fma_f32 v239, v239, s75, -v223
	v_exp_f32_e32 v239, v239
	v_add_f32_e32 v193, v238, v193
	v_fma_f32 v240, v240, s75, -v223
	v_exp_f32_e32 v240, v240
	v_add_f32_e32 v194, v239, v194
	v_fma_f32 v241, v241, s75, -v223
	v_exp_f32_e32 v241, v241
	v_add_f32_e32 v193, v240, v193
	v_add_f32_e32 v194, v241, v194
	v_add_f32_e32 v193, v193, v194
	v_cvt_pk_bf16_f32 v242, v226, v227
	v_cvt_pk_bf16_f32 v243, v228, v229
	v_cvt_pk_bf16_f32 v244, v230, v231
	v_cvt_pk_bf16_f32 v245, v232, v233
	v_cvt_pk_bf16_f32 v246, v234, v235
	v_cvt_pk_bf16_f32 v247, v236, v237
	v_cvt_pk_bf16_f32 v248, v238, v239
	v_cvt_pk_bf16_f32 v249, v240, v241
	v_add_f32_e32 v155, v155, v193
	s_nop 1
	v_mfma_f32_32x32x16_bf16 v[34:49], v[142:145], v[242:245], v[34:49]
	v_max3_f32 v185, v66, v67, v68
	v_mfma_f32_32x32x16_bf16 v[2:17], v[134:137], v[242:245], v[2:17]
	ds_read_b128 v[242:245], v161 offset:4672
	v_max3_f32 v185, v185, v69, v70
	v_max3_f32 v185, v185, v71, v72
	v_mfma_f32_32x32x16_bf16 v[34:49], v[138:141], v[246:249], v[34:49]
	v_max3_f32 v185, v185, v73, v74
	v_max3_f32 v185, v185, v75, v76
	v_mfma_f32_32x32x16_bf16 v[2:17], v[130:133], v[246:249], v[2:17]
	ds_read_b128 v[246:249], v161 offset:4704
	ds_read2_b64 v[142:145], v163 offset0:8 offset1:10
	ds_read2_b64 v[138:141], v163 offset0:12 offset1:14
	ds_read2_b64 v[134:137], v250 offset0:40 offset1:42
	ds_read2_b64 v[130:133], v250 offset0:44 offset1:46
	v_max3_f32 v185, v185, v77, v78
	v_max3_f32 v185, v185, v79, v80
	v_max_f32_e32 v185, v185, v81
	v_mov_b32_e32 v188, v185
	s_nop 1
	v_permlane32_swap_b32_e32 v185, v188
	v_max_f32_e32 v185, v185, v188
	v_fma_f32 v188, v185, s75, -v224
	v_cmp_lt_f32_e32 vcc, s73, v188
	s_cbranch_vccz .Lda_dl_nr2
	v_mul_f32_e32 v185, 0x3e8293ee, v185
	v_max_f32_e32 v185, v224, v185
	v_sub_f32_e32 v188, v224, v185
	v_exp_f32_e32 v188, v188
	v_mov_b32_e32 v224, v185
	s_nop 0
	v_mul_f32_e32 v157, v157, v188
	v_pk_mul_f32 v[50:51], v[50:51], v[188:189] op_sel_hi:[1,0]
	v_pk_mul_f32 v[52:53], v[52:53], v[188:189] op_sel_hi:[1,0]
	v_pk_mul_f32 v[54:55], v[54:55], v[188:189] op_sel_hi:[1,0]
	v_pk_mul_f32 v[56:57], v[56:57], v[188:189] op_sel_hi:[1,0]
	v_pk_mul_f32 v[58:59], v[58:59], v[188:189] op_sel_hi:[1,0]
	v_pk_mul_f32 v[60:61], v[60:61], v[188:189] op_sel_hi:[1,0]
	v_pk_mul_f32 v[62:63], v[62:63], v[188:189] op_sel_hi:[1,0]
	v_pk_mul_f32 v[64:65], v[64:65], v[188:189] op_sel_hi:[1,0]
	v_pk_mul_f32 v[18:19], v[18:19], v[188:189] op_sel_hi:[1,0]
	v_pk_mul_f32 v[20:21], v[20:21], v[188:189] op_sel_hi:[1,0]
	v_pk_mul_f32 v[22:23], v[22:23], v[188:189] op_sel_hi:[1,0]
	v_pk_mul_f32 v[24:25], v[24:25], v[188:189] op_sel_hi:[1,0]
	v_pk_mul_f32 v[26:27], v[26:27], v[188:189] op_sel_hi:[1,0]
	v_pk_mul_f32 v[28:29], v[28:29], v[188:189] op_sel_hi:[1,0]
	v_pk_mul_f32 v[30:31], v[30:31], v[188:189] op_sel_hi:[1,0]
	v_pk_mul_f32 v[32:33], v[32:33], v[188:189] op_sel_hi:[1,0]
.Lda_dl_nr2:
	v_fma_f32 v66, v66, s75, -v224
	v_exp_f32_e32 v66, v66
	v_fma_f32 v67, v67, s75, -v224
	v_exp_f32_e32 v67, v67
	v_mov_b32_e32 v193, v66
	v_fma_f32 v68, v68, s75, -v224
	v_exp_f32_e32 v68, v68
	v_mov_b32_e32 v194, v67
	v_fma_f32 v69, v69, s75, -v224
	v_exp_f32_e32 v69, v69
	v_add_f32_e32 v193, v68, v193
	v_fma_f32 v70, v70, s75, -v224
	s_waitcnt lgkmcnt(4)
	v_mfma_f32_32x32x16_bf16 v[226:241], v[242:245], v[90:93], 0
	v_exp_f32_e32 v70, v70
	v_add_f32_e32 v194, v69, v194
	v_fma_f32 v71, v71, s75, -v224
	v_exp_f32_e32 v71, v71
	v_add_f32_e32 v193, v70, v193
	v_fma_f32 v72, v72, s75, -v224
	v_exp_f32_e32 v72, v72
	v_add_f32_e32 v194, v71, v194
	v_fma_f32 v73, v73, s75, -v224
	v_exp_f32_e32 v73, v73
	v_add_f32_e32 v193, v72, v193
	v_fma_f32 v74, v74, s75, -v224
	v_exp_f32_e32 v74, v74
	v_add_f32_e32 v194, v73, v194
	v_fma_f32 v75, v75, s75, -v224
	v_exp_f32_e32 v75, v75
	v_add_f32_e32 v193, v74, v193
	v_fma_f32 v76, v76, s75, -v224
	v_mfma_f32_32x32x16_bf16 v[226:241], v[246:249], v[94:97], v[226:241]
	v_exp_f32_e32 v76, v76
	v_add_f32_e32 v194, v75, v194
	v_fma_f32 v77, v77, s75, -v224
	v_exp_f32_e32 v77, v77
	v_add_f32_e32 v193, v76, v193
	v_fma_f32 v78, v78, s75, -v224
	v_exp_f32_e32 v78, v78
	v_add_f32_e32 v194, v77, v194
	v_fma_f32 v79, v79, s75, -v224
	v_exp_f32_e32 v79, v79
	v_add_f32_e32 v193, v78, v193
	v_fma_f32 v80, v80, s75, -v224
	v_exp_f32_e32 v80, v80
	v_add_f32_e32 v194, v79, v194
	v_fma_f32 v81, v81, s75, -v224
	v_exp_f32_e32 v81, v81
	v_add_f32_e32 v193, v80, v193
	v_add_f32_e32 v194, v81, v194
	v_add_f32_e32 v193, v193, v194
	v_cvt_pk_bf16_f32 v242, v66, v67
	v_cvt_pk_bf16_f32 v243, v68, v69
	v_cvt_pk_bf16_f32 v244, v70, v71
	v_cvt_pk_bf16_f32 v245, v72, v73
	v_cvt_pk_bf16_f32 v246, v74, v75
	v_cvt_pk_bf16_f32 v247, v76, v77
	v_cvt_pk_bf16_f32 v248, v78, v79
	v_cvt_pk_bf16_f32 v249, v80, v81
	v_add_f32_e32 v157, v157, v193
	s_waitcnt lgkmcnt(0)
	s_nop 1
	v_mfma_f32_32x32x16_bf16 v[50:65], v[142:145], v[242:245], v[50:65]
	v_max3_f32 v185, v226, v227, v228
	v_mfma_f32_32x32x16_bf16 v[18:33], v[134:137], v[242:245], v[18:33]
	ds_read_b128 v[242:245], v161 offset:9216
	v_max3_f32 v185, v185, v229, v230
	v_max3_f32 v185, v185, v231, v232
	v_mfma_f32_32x32x16_bf16 v[50:65], v[138:141], v[246:249], v[50:65]
	v_max3_f32 v185, v185, v233, v234
	v_max3_f32 v185, v185, v235, v236
	v_mfma_f32_32x32x16_bf16 v[18:33], v[130:133], v[246:249], v[18:33]
	ds_read_b128 v[246:249], v161 offset:9248
	v_max3_f32 v185, v185, v237, v238
	v_max3_f32 v185, v185, v239, v240
	v_max_f32_e32 v185, v185, v241
	v_mov_b32_e32 v188, v185
	s_nop 1
	v_permlane32_swap_b32_e32 v185, v188
	v_max_f32_e32 v185, v185, v188
	v_fma_f32 v188, v185, s75, -v223
	v_cmp_lt_f32_e32 vcc, s73, v188
	s_cbranch_vccz .Lda_dl_nr3
	v_mul_f32_e32 v185, 0x3e8293ee, v185
	v_max_f32_e32 v185, v223, v185
	v_sub_f32_e32 v188, v223, v185
	v_exp_f32_e32 v188, v188
	v_mov_b32_e32 v223, v185
	s_nop 0
	v_mul_f32_e32 v155, v155, v188
	v_pk_mul_f32 v[34:35], v[34:35], v[188:189] op_sel_hi:[1,0]
	v_pk_mul_f32 v[36:37], v[36:37], v[188:189] op_sel_hi:[1,0]
	v_pk_mul_f32 v[38:39], v[38:39], v[188:189] op_sel_hi:[1,0]
	v_pk_mul_f32 v[40:41], v[40:41], v[188:189] op_sel_hi:[1,0]
	v_pk_mul_f32 v[42:43], v[42:43], v[188:189] op_sel_hi:[1,0]
	v_pk_mul_f32 v[44:45], v[44:45], v[188:189] op_sel_hi:[1,0]
	v_pk_mul_f32 v[46:47], v[46:47], v[188:189] op_sel_hi:[1,0]
	v_pk_mul_f32 v[48:49], v[48:49], v[188:189] op_sel_hi:[1,0]
	v_pk_mul_f32 v[2:3], v[2:3], v[188:189] op_sel_hi:[1,0]
	v_pk_mul_f32 v[4:5], v[4:5], v[188:189] op_sel_hi:[1,0]
	v_pk_mul_f32 v[6:7], v[6:7], v[188:189] op_sel_hi:[1,0]
	v_pk_mul_f32 v[8:9], v[8:9], v[188:189] op_sel_hi:[1,0]
	v_pk_mul_f32 v[10:11], v[10:11], v[188:189] op_sel_hi:[1,0]
	v_pk_mul_f32 v[12:13], v[12:13], v[188:189] op_sel_hi:[1,0]
	v_pk_mul_f32 v[14:15], v[14:15], v[188:189] op_sel_hi:[1,0]
	v_pk_mul_f32 v[16:17], v[16:17], v[188:189] op_sel_hi:[1,0]
.Lda_dl_nr3:
	v_fma_f32 v226, v226, s75, -v223
	v_exp_f32_e32 v226, v226
	v_fma_f32 v227, v227, s75, -v223
	v_exp_f32_e32 v227, v227
	v_mov_b32_e32 v193, v226
	v_fma_f32 v228, v228, s75, -v223
	v_exp_f32_e32 v228, v228
	v_mov_b32_e32 v194, v227
	v_fma_f32 v229, v229, s75, -v223
	v_exp_f32_e32 v229, v229
	v_add_f32_e32 v193, v228, v193
	v_fma_f32 v230, v230, s75, -v223
	s_waitcnt lgkmcnt(0)
	v_mfma_f32_32x32x16_bf16 v[66:81], v[242:245], v[82:85], 0
	v_exp_f32_e32 v230, v230
	v_add_f32_e32 v194, v229, v194
	v_fma_f32 v231, v231, s75, -v223
	v_exp_f32_e32 v231, v231
	v_add_f32_e32 v193, v230, v193
	v_fma_f32 v232, v232, s75, -v223
	v_exp_f32_e32 v232, v232
	v_add_f32_e32 v194, v231, v194
	v_fma_f32 v233, v233, s75, -v223
	v_exp_f32_e32 v233, v233
	v_add_f32_e32 v193, v232, v193
	v_fma_f32 v234, v234, s75, -v223
	v_exp_f32_e32 v234, v234
	v_add_f32_e32 v194, v233, v194
	v_fma_f32 v235, v235, s75, -v223
	v_exp_f32_e32 v235, v235
	v_add_f32_e32 v193, v234, v193
	v_fma_f32 v236, v236, s75, -v223
	v_mfma_f32_32x32x16_bf16 v[66:81], v[246:249], v[86:89], v[66:81]
	v_exp_f32_e32 v236, v236
	v_add_f32_e32 v194, v235, v194
	v_fma_f32 v237, v237, s75, -v223
	v_exp_f32_e32 v237, v237
	v_add_f32_e32 v193, v236, v193
	v_fma_f32 v238, v238, s75, -v223
	v_exp_f32_e32 v238, v238
	v_add_f32_e32 v194, v237, v194
	v_fma_f32 v239, v239, s75, -v223
	v_exp_f32_e32 v239, v239
	v_add_f32_e32 v193, v238, v193
	v_fma_f32 v240, v240, s75, -v223
	v_exp_f32_e32 v240, v240
	v_add_f32_e32 v194, v239, v194
	v_fma_f32 v241, v241, s75, -v223
	v_exp_f32_e32 v241, v241
	v_add_f32_e32 v193, v240, v193
	v_add_f32_e32 v194, v241, v194
	v_add_f32_e32 v193, v193, v194
	v_cvt_pk_bf16_f32 v242, v226, v227
	v_cvt_pk_bf16_f32 v243, v228, v229
	v_cvt_pk_bf16_f32 v244, v230, v231
	v_cvt_pk_bf16_f32 v245, v232, v233
	v_cvt_pk_bf16_f32 v246, v234, v235
	v_cvt_pk_bf16_f32 v247, v236, v237
	v_cvt_pk_bf16_f32 v248, v238, v239
	v_cvt_pk_bf16_f32 v249, v240, v241
	v_add_f32_e32 v155, v155, v193
	s_nop 1
	v_mfma_f32_32x32x16_bf16 v[34:49], v[142:145], v[242:245], v[34:49]
	v_max3_f32 v185, v66, v67, v68
	v_mfma_f32_32x32x16_bf16 v[2:17], v[134:137], v[242:245], v[2:17]
	ds_read_b128 v[242:245], v161 offset:9280
	v_max3_f32 v185, v185, v69, v70
	v_max3_f32 v185, v185, v71, v72
	v_mfma_f32_32x32x16_bf16 v[34:49], v[138:141], v[246:249], v[34:49]
	v_max3_f32 v185, v185, v73, v74
	v_max3_f32 v185, v185, v75, v76
	v_mfma_f32_32x32x16_bf16 v[2:17], v[130:133], v[246:249], v[2:17]
	ds_read_b128 v[246:249], v161 offset:9312
	ds_read2_b64 v[142:145], v163 offset0:16 offset1:18
	ds_read2_b64 v[138:141], v163 offset0:20 offset1:22
	ds_read2_b64 v[134:137], v250 offset0:48 offset1:50
	ds_read2_b64 v[130:133], v250 offset0:52 offset1:54
	v_max3_f32 v185, v185, v77, v78
	v_max3_f32 v185, v185, v79, v80
	v_max_f32_e32 v185, v185, v81
	v_mov_b32_e32 v188, v185
	s_nop 1
	v_permlane32_swap_b32_e32 v185, v188
	v_max_f32_e32 v185, v185, v188
	v_fma_f32 v188, v185, s75, -v224
	v_cmp_lt_f32_e32 vcc, s73, v188
	s_cbranch_vccz .Lda_dl_nr4
	v_mul_f32_e32 v185, 0x3e8293ee, v185
	v_max_f32_e32 v185, v224, v185
	v_sub_f32_e32 v188, v224, v185
	v_exp_f32_e32 v188, v188
	v_mov_b32_e32 v224, v185
	s_nop 0
	v_mul_f32_e32 v157, v157, v188
	v_pk_mul_f32 v[50:51], v[50:51], v[188:189] op_sel_hi:[1,0]
	v_pk_mul_f32 v[52:53], v[52:53], v[188:189] op_sel_hi:[1,0]
	v_pk_mul_f32 v[54:55], v[54:55], v[188:189] op_sel_hi:[1,0]
	v_pk_mul_f32 v[56:57], v[56:57], v[188:189] op_sel_hi:[1,0]
	v_pk_mul_f32 v[58:59], v[58:59], v[188:189] op_sel_hi:[1,0]
	v_pk_mul_f32 v[60:61], v[60:61], v[188:189] op_sel_hi:[1,0]
	v_pk_mul_f32 v[62:63], v[62:63], v[188:189] op_sel_hi:[1,0]
	v_pk_mul_f32 v[64:65], v[64:65], v[188:189] op_sel_hi:[1,0]
	v_pk_mul_f32 v[18:19], v[18:19], v[188:189] op_sel_hi:[1,0]
	v_pk_mul_f32 v[20:21], v[20:21], v[188:189] op_sel_hi:[1,0]
	v_pk_mul_f32 v[22:23], v[22:23], v[188:189] op_sel_hi:[1,0]
	v_pk_mul_f32 v[24:25], v[24:25], v[188:189] op_sel_hi:[1,0]
	v_pk_mul_f32 v[26:27], v[26:27], v[188:189] op_sel_hi:[1,0]
	v_pk_mul_f32 v[28:29], v[28:29], v[188:189] op_sel_hi:[1,0]
	v_pk_mul_f32 v[30:31], v[30:31], v[188:189] op_sel_hi:[1,0]
	v_pk_mul_f32 v[32:33], v[32:33], v[188:189] op_sel_hi:[1,0]
.Lda_dl_nr4:
	v_fma_f32 v66, v66, s75, -v224
	v_exp_f32_e32 v66, v66
	v_fma_f32 v67, v67, s75, -v224
	v_exp_f32_e32 v67, v67
	v_mov_b32_e32 v193, v66
	v_fma_f32 v68, v68, s75, -v224
	v_exp_f32_e32 v68, v68
	v_mov_b32_e32 v194, v67
	v_fma_f32 v69, v69, s75, -v224
	v_exp_f32_e32 v69, v69
	v_add_f32_e32 v193, v68, v193
	v_fma_f32 v70, v70, s75, -v224
	s_waitcnt lgkmcnt(4)
	v_mfma_f32_32x32x16_bf16 v[226:241], v[242:245], v[90:93], 0
	v_exp_f32_e32 v70, v70
	v_add_f32_e32 v194, v69, v194
	v_fma_f32 v71, v71, s75, -v224
	v_exp_f32_e32 v71, v71
	v_add_f32_e32 v193, v70, v193
	v_fma_f32 v72, v72, s75, -v224
	v_exp_f32_e32 v72, v72
	v_add_f32_e32 v194, v71, v194
	v_fma_f32 v73, v73, s75, -v224
	v_exp_f32_e32 v73, v73
	v_add_f32_e32 v193, v72, v193
	v_fma_f32 v74, v74, s75, -v224
	v_exp_f32_e32 v74, v74
	v_add_f32_e32 v194, v73, v194
	v_fma_f32 v75, v75, s75, -v224
	v_exp_f32_e32 v75, v75
	v_add_f32_e32 v193, v74, v193
	v_fma_f32 v76, v76, s75, -v224
	v_mfma_f32_32x32x16_bf16 v[226:241], v[246:249], v[94:97], v[226:241]
	v_exp_f32_e32 v76, v76
	v_add_f32_e32 v194, v75, v194
	v_fma_f32 v77, v77, s75, -v224
	v_exp_f32_e32 v77, v77
	v_add_f32_e32 v193, v76, v193
	v_fma_f32 v78, v78, s75, -v224
	v_exp_f32_e32 v78, v78
	v_add_f32_e32 v194, v77, v194
	v_fma_f32 v79, v79, s75, -v224
	v_exp_f32_e32 v79, v79
	v_add_f32_e32 v193, v78, v193
	v_fma_f32 v80, v80, s75, -v224
	v_exp_f32_e32 v80, v80
	v_add_f32_e32 v194, v79, v194
	v_fma_f32 v81, v81, s75, -v224
	v_exp_f32_e32 v81, v81
	v_add_f32_e32 v193, v80, v193
	v_add_f32_e32 v194, v81, v194
	v_add_f32_e32 v193, v193, v194
	v_cvt_pk_bf16_f32 v242, v66, v67
	v_cvt_pk_bf16_f32 v243, v68, v69
	v_cvt_pk_bf16_f32 v244, v70, v71
	v_cvt_pk_bf16_f32 v245, v72, v73
	v_cvt_pk_bf16_f32 v246, v74, v75
	v_cvt_pk_bf16_f32 v247, v76, v77
	v_cvt_pk_bf16_f32 v248, v78, v79
	v_cvt_pk_bf16_f32 v249, v80, v81
	v_add_f32_e32 v157, v157, v193
	s_waitcnt lgkmcnt(0)
	s_nop 1
	v_mfma_f32_32x32x16_bf16 v[50:65], v[142:145], v[242:245], v[50:65]
	v_max3_f32 v185, v226, v227, v228
	v_mfma_f32_32x32x16_bf16 v[18:33], v[134:137], v[242:245], v[18:33]
	ds_read_b128 v[242:245], v161 offset:13824
	v_max3_f32 v185, v185, v229, v230
	v_max3_f32 v185, v185, v231, v232
	v_mfma_f32_32x32x16_bf16 v[50:65], v[138:141], v[246:249], v[50:65]
	v_max3_f32 v185, v185, v233, v234
	v_max3_f32 v185, v185, v235, v236
	v_mfma_f32_32x32x16_bf16 v[18:33], v[130:133], v[246:249], v[18:33]
	ds_read_b128 v[246:249], v161 offset:13856
	v_max3_f32 v185, v185, v237, v238
	v_max3_f32 v185, v185, v239, v240
	v_max_f32_e32 v185, v185, v241
	v_mov_b32_e32 v188, v185
	s_nop 1
	v_permlane32_swap_b32_e32 v185, v188
	v_max_f32_e32 v185, v185, v188
	v_fma_f32 v188, v185, s75, -v223
	v_cmp_lt_f32_e32 vcc, s73, v188
	s_cbranch_vccz .Lda_dl_nr5
	v_mul_f32_e32 v185, 0x3e8293ee, v185
	v_max_f32_e32 v185, v223, v185
	v_sub_f32_e32 v188, v223, v185
	v_exp_f32_e32 v188, v188
	v_mov_b32_e32 v223, v185
	s_nop 0
	v_mul_f32_e32 v155, v155, v188
	v_pk_mul_f32 v[34:35], v[34:35], v[188:189] op_sel_hi:[1,0]
	v_pk_mul_f32 v[36:37], v[36:37], v[188:189] op_sel_hi:[1,0]
	v_pk_mul_f32 v[38:39], v[38:39], v[188:189] op_sel_hi:[1,0]
	v_pk_mul_f32 v[40:41], v[40:41], v[188:189] op_sel_hi:[1,0]
	v_pk_mul_f32 v[42:43], v[42:43], v[188:189] op_sel_hi:[1,0]
	v_pk_mul_f32 v[44:45], v[44:45], v[188:189] op_sel_hi:[1,0]
	v_pk_mul_f32 v[46:47], v[46:47], v[188:189] op_sel_hi:[1,0]
	v_pk_mul_f32 v[48:49], v[48:49], v[188:189] op_sel_hi:[1,0]
	v_pk_mul_f32 v[2:3], v[2:3], v[188:189] op_sel_hi:[1,0]
	v_pk_mul_f32 v[4:5], v[4:5], v[188:189] op_sel_hi:[1,0]
	v_pk_mul_f32 v[6:7], v[6:7], v[188:189] op_sel_hi:[1,0]
	v_pk_mul_f32 v[8:9], v[8:9], v[188:189] op_sel_hi:[1,0]
	v_pk_mul_f32 v[10:11], v[10:11], v[188:189] op_sel_hi:[1,0]
	v_pk_mul_f32 v[12:13], v[12:13], v[188:189] op_sel_hi:[1,0]
	v_pk_mul_f32 v[14:15], v[14:15], v[188:189] op_sel_hi:[1,0]
	v_pk_mul_f32 v[16:17], v[16:17], v[188:189] op_sel_hi:[1,0]
.Lda_dl_nr5:
	v_fma_f32 v226, v226, s75, -v223
	v_exp_f32_e32 v226, v226
	v_fma_f32 v227, v227, s75, -v223
	v_exp_f32_e32 v227, v227
	v_mov_b32_e32 v193, v226
	v_fma_f32 v228, v228, s75, -v223
	v_exp_f32_e32 v228, v228
	v_mov_b32_e32 v194, v227
	v_fma_f32 v229, v229, s75, -v223
	v_exp_f32_e32 v229, v229
	v_add_f32_e32 v193, v228, v193
	v_fma_f32 v230, v230, s75, -v223
	s_waitcnt lgkmcnt(0)
	v_mfma_f32_32x32x16_bf16 v[66:81], v[242:245], v[82:85], 0
	v_exp_f32_e32 v230, v230
	v_add_f32_e32 v194, v229, v194
	v_fma_f32 v231, v231, s75, -v223
	v_exp_f32_e32 v231, v231
	v_add_f32_e32 v193, v230, v193
	v_fma_f32 v232, v232, s75, -v223
	v_exp_f32_e32 v232, v232
	v_add_f32_e32 v194, v231, v194
	v_fma_f32 v233, v233, s75, -v223
	v_exp_f32_e32 v233, v233
	v_add_f32_e32 v193, v232, v193
	v_fma_f32 v234, v234, s75, -v223
	v_exp_f32_e32 v234, v234
	v_add_f32_e32 v194, v233, v194
	v_fma_f32 v235, v235, s75, -v223
	v_exp_f32_e32 v235, v235
	v_add_f32_e32 v193, v234, v193
	v_fma_f32 v236, v236, s75, -v223
	v_mfma_f32_32x32x16_bf16 v[66:81], v[246:249], v[86:89], v[66:81]
	v_exp_f32_e32 v236, v236
	v_add_f32_e32 v194, v235, v194
	v_fma_f32 v237, v237, s75, -v223
	v_exp_f32_e32 v237, v237
	v_add_f32_e32 v193, v236, v193
	v_fma_f32 v238, v238, s75, -v223
	v_exp_f32_e32 v238, v238
	v_add_f32_e32 v194, v237, v194
	v_fma_f32 v239, v239, s75, -v223
	v_exp_f32_e32 v239, v239
	v_add_f32_e32 v193, v238, v193
	v_fma_f32 v240, v240, s75, -v223
	v_exp_f32_e32 v240, v240
	v_add_f32_e32 v194, v239, v194
	v_fma_f32 v241, v241, s75, -v223
	v_exp_f32_e32 v241, v241
	v_add_f32_e32 v193, v240, v193
	v_add_f32_e32 v194, v241, v194
	v_add_f32_e32 v193, v193, v194
	v_cvt_pk_bf16_f32 v242, v226, v227
	v_cvt_pk_bf16_f32 v243, v228, v229
	v_cvt_pk_bf16_f32 v244, v230, v231
	v_cvt_pk_bf16_f32 v245, v232, v233
	v_cvt_pk_bf16_f32 v246, v234, v235
	v_cvt_pk_bf16_f32 v247, v236, v237
	v_cvt_pk_bf16_f32 v248, v238, v239
	v_cvt_pk_bf16_f32 v249, v240, v241
	v_add_f32_e32 v155, v155, v193
	s_nop 1
	v_mfma_f32_32x32x16_bf16 v[34:49], v[142:145], v[242:245], v[34:49]
	v_max3_f32 v185, v66, v67, v68
	v_mfma_f32_32x32x16_bf16 v[2:17], v[134:137], v[242:245], v[2:17]
	ds_read_b128 v[242:245], v161 offset:13888
	v_max3_f32 v185, v185, v69, v70
	v_max3_f32 v185, v185, v71, v72
	v_mfma_f32_32x32x16_bf16 v[34:49], v[138:141], v[246:249], v[34:49]
	v_max3_f32 v185, v185, v73, v74
	v_max3_f32 v185, v185, v75, v76
	v_mfma_f32_32x32x16_bf16 v[2:17], v[130:133], v[246:249], v[2:17]
	ds_read_b128 v[246:249], v161 offset:13920
	ds_read2_b64 v[142:145], v163 offset0:24 offset1:26
	ds_read2_b64 v[138:141], v163 offset0:28 offset1:30
	ds_read2_b64 v[134:137], v250 offset0:56 offset1:58
	ds_read2_b64 v[130:133], v250 offset0:60 offset1:62
	v_max3_f32 v185, v185, v77, v78
	v_max3_f32 v185, v185, v79, v80
	v_max_f32_e32 v185, v185, v81
	v_mov_b32_e32 v188, v185
	s_nop 1
	v_permlane32_swap_b32_e32 v185, v188
	v_max_f32_e32 v185, v185, v188
	v_fma_f32 v188, v185, s75, -v224
	v_cmp_lt_f32_e32 vcc, s73, v188
	s_cbranch_vccz .Lda_dl_nr6
	v_mul_f32_e32 v185, 0x3e8293ee, v185
	v_max_f32_e32 v185, v224, v185
	v_sub_f32_e32 v188, v224, v185
	v_exp_f32_e32 v188, v188
	v_mov_b32_e32 v224, v185
	s_nop 0
	v_mul_f32_e32 v157, v157, v188
	v_pk_mul_f32 v[50:51], v[50:51], v[188:189] op_sel_hi:[1,0]
	v_pk_mul_f32 v[52:53], v[52:53], v[188:189] op_sel_hi:[1,0]
	v_pk_mul_f32 v[54:55], v[54:55], v[188:189] op_sel_hi:[1,0]
	v_pk_mul_f32 v[56:57], v[56:57], v[188:189] op_sel_hi:[1,0]
	v_pk_mul_f32 v[58:59], v[58:59], v[188:189] op_sel_hi:[1,0]
	v_pk_mul_f32 v[60:61], v[60:61], v[188:189] op_sel_hi:[1,0]
	v_pk_mul_f32 v[62:63], v[62:63], v[188:189] op_sel_hi:[1,0]
	v_pk_mul_f32 v[64:65], v[64:65], v[188:189] op_sel_hi:[1,0]
	v_pk_mul_f32 v[18:19], v[18:19], v[188:189] op_sel_hi:[1,0]
	v_pk_mul_f32 v[20:21], v[20:21], v[188:189] op_sel_hi:[1,0]
	v_pk_mul_f32 v[22:23], v[22:23], v[188:189] op_sel_hi:[1,0]
	v_pk_mul_f32 v[24:25], v[24:25], v[188:189] op_sel_hi:[1,0]
	v_pk_mul_f32 v[26:27], v[26:27], v[188:189] op_sel_hi:[1,0]
	v_pk_mul_f32 v[28:29], v[28:29], v[188:189] op_sel_hi:[1,0]
	v_pk_mul_f32 v[30:31], v[30:31], v[188:189] op_sel_hi:[1,0]
	v_pk_mul_f32 v[32:33], v[32:33], v[188:189] op_sel_hi:[1,0]
.Lda_dl_nr6:
	v_fma_f32 v66, v66, s75, -v224
	v_exp_f32_e32 v66, v66
	v_fma_f32 v67, v67, s75, -v224
	v_exp_f32_e32 v67, v67
	v_mov_b32_e32 v193, v66
	v_fma_f32 v68, v68, s75, -v224
	v_exp_f32_e32 v68, v68
	v_mov_b32_e32 v194, v67
	v_fma_f32 v69, v69, s75, -v224
	v_exp_f32_e32 v69, v69
	v_add_f32_e32 v193, v68, v193
	v_fma_f32 v70, v70, s75, -v224
	s_waitcnt lgkmcnt(4)
	v_mfma_f32_32x32x16_bf16 v[226:241], v[242:245], v[90:93], 0
	v_exp_f32_e32 v70, v70
	v_add_f32_e32 v194, v69, v194
	v_fma_f32 v71, v71, s75, -v224
	v_exp_f32_e32 v71, v71
	v_add_f32_e32 v193, v70, v193
	v_fma_f32 v72, v72, s75, -v224
	v_exp_f32_e32 v72, v72
	v_add_f32_e32 v194, v71, v194
	v_fma_f32 v73, v73, s75, -v224
	v_exp_f32_e32 v73, v73
	v_add_f32_e32 v193, v72, v193
	v_fma_f32 v74, v74, s75, -v224
	v_exp_f32_e32 v74, v74
	v_add_f32_e32 v194, v73, v194
	v_fma_f32 v75, v75, s75, -v224
	v_exp_f32_e32 v75, v75
	v_add_f32_e32 v193, v74, v193
	v_fma_f32 v76, v76, s75, -v224
	v_mfma_f32_32x32x16_bf16 v[226:241], v[246:249], v[94:97], v[226:241]
	v_exp_f32_e32 v76, v76
	v_add_f32_e32 v194, v75, v194
	v_fma_f32 v77, v77, s75, -v224
	v_exp_f32_e32 v77, v77
	v_add_f32_e32 v193, v76, v193
	v_fma_f32 v78, v78, s75, -v224
	v_exp_f32_e32 v78, v78
	v_add_f32_e32 v194, v77, v194
	v_fma_f32 v79, v79, s75, -v224
	v_exp_f32_e32 v79, v79
	v_add_f32_e32 v193, v78, v193
	v_fma_f32 v80, v80, s75, -v224
	v_exp_f32_e32 v80, v80
	v_add_f32_e32 v194, v79, v194
	v_fma_f32 v81, v81, s75, -v224
	v_exp_f32_e32 v81, v81
	v_add_f32_e32 v193, v80, v193
	v_add_f32_e32 v194, v81, v194
	v_add_f32_e32 v193, v193, v194
	v_cvt_pk_bf16_f32 v242, v66, v67
	v_cvt_pk_bf16_f32 v243, v68, v69
	v_cvt_pk_bf16_f32 v244, v70, v71
	v_cvt_pk_bf16_f32 v245, v72, v73
	v_cvt_pk_bf16_f32 v246, v74, v75
	v_cvt_pk_bf16_f32 v247, v76, v77
	v_cvt_pk_bf16_f32 v248, v78, v79
	v_cvt_pk_bf16_f32 v249, v80, v81
	v_add_f32_e32 v157, v157, v193
	s_waitcnt lgkmcnt(0)
	s_nop 1
	v_mfma_f32_32x32x16_bf16 v[50:65], v[142:145], v[242:245], v[50:65]
	v_max3_f32 v185, v226, v227, v228
	v_mfma_f32_32x32x16_bf16 v[18:33], v[134:137], v[242:245], v[18:33]
	v_max3_f32 v185, v185, v229, v230
	v_max3_f32 v185, v185, v231, v232
	v_mfma_f32_32x32x16_bf16 v[50:65], v[138:141], v[246:249], v[50:65]
	v_max3_f32 v185, v185, v233, v234
	v_max3_f32 v185, v185, v235, v236
	v_mfma_f32_32x32x16_bf16 v[18:33], v[130:133], v[246:249], v[18:33]
	v_max3_f32 v185, v185, v237, v238
	v_max3_f32 v185, v185, v239, v240
	v_max_f32_e32 v185, v185, v241
	v_mov_b32_e32 v188, v185
	s_nop 1
	v_permlane32_swap_b32_e32 v185, v188
	v_max_f32_e32 v185, v185, v188
	v_fma_f32 v188, v185, s75, -v223
	v_cmp_lt_f32_e32 vcc, s73, v188
	s_cbranch_vccz .Lda_dl_nr7
	v_mul_f32_e32 v185, 0x3e8293ee, v185
	v_max_f32_e32 v185, v223, v185
	v_sub_f32_e32 v188, v223, v185
	v_exp_f32_e32 v188, v188
	v_mov_b32_e32 v223, v185
	s_nop 0
	v_mul_f32_e32 v155, v155, v188
	v_pk_mul_f32 v[34:35], v[34:35], v[188:189] op_sel_hi:[1,0]
	v_pk_mul_f32 v[36:37], v[36:37], v[188:189] op_sel_hi:[1,0]
	v_pk_mul_f32 v[38:39], v[38:39], v[188:189] op_sel_hi:[1,0]
	v_pk_mul_f32 v[40:41], v[40:41], v[188:189] op_sel_hi:[1,0]
	v_pk_mul_f32 v[42:43], v[42:43], v[188:189] op_sel_hi:[1,0]
	v_pk_mul_f32 v[44:45], v[44:45], v[188:189] op_sel_hi:[1,0]
	v_pk_mul_f32 v[46:47], v[46:47], v[188:189] op_sel_hi:[1,0]
	v_pk_mul_f32 v[48:49], v[48:49], v[188:189] op_sel_hi:[1,0]
	v_pk_mul_f32 v[2:3], v[2:3], v[188:189] op_sel_hi:[1,0]
	v_pk_mul_f32 v[4:5], v[4:5], v[188:189] op_sel_hi:[1,0]
	v_pk_mul_f32 v[6:7], v[6:7], v[188:189] op_sel_hi:[1,0]
	v_pk_mul_f32 v[8:9], v[8:9], v[188:189] op_sel_hi:[1,0]
	v_pk_mul_f32 v[10:11], v[10:11], v[188:189] op_sel_hi:[1,0]
	v_pk_mul_f32 v[12:13], v[12:13], v[188:189] op_sel_hi:[1,0]
	v_pk_mul_f32 v[14:15], v[14:15], v[188:189] op_sel_hi:[1,0]
	v_pk_mul_f32 v[16:17], v[16:17], v[188:189] op_sel_hi:[1,0]
.Lda_dl_nr7:
	v_fma_f32 v226, v226, s75, -v223
	v_exp_f32_e32 v226, v226
	v_fma_f32 v227, v227, s75, -v223
	v_exp_f32_e32 v227, v227
	v_mov_b32_e32 v193, v226
	v_fma_f32 v228, v228, s75, -v223
	v_exp_f32_e32 v228, v228
	v_mov_b32_e32 v194, v227
	v_fma_f32 v229, v229, s75, -v223
	v_exp_f32_e32 v229, v229
	v_add_f32_e32 v193, v228, v193
	v_fma_f32 v230, v230, s75, -v223
	v_exp_f32_e32 v230, v230
	v_add_f32_e32 v194, v229, v194
	v_fma_f32 v231, v231, s75, -v223
	v_exp_f32_e32 v231, v231
	v_add_f32_e32 v193, v230, v193
	v_fma_f32 v232, v232, s75, -v223
	v_exp_f32_e32 v232, v232
	v_add_f32_e32 v194, v231, v194
	v_fma_f32 v233, v233, s75, -v223
	v_exp_f32_e32 v233, v233
	v_add_f32_e32 v193, v232, v193
	v_fma_f32 v234, v234, s75, -v223
	v_exp_f32_e32 v234, v234
	v_add_f32_e32 v194, v233, v194
	v_fma_f32 v235, v235, s75, -v223
	v_exp_f32_e32 v235, v235
	v_add_f32_e32 v193, v234, v193
	v_fma_f32 v236, v236, s75, -v223
	v_exp_f32_e32 v236, v236
	v_add_f32_e32 v194, v235, v194
	v_fma_f32 v237, v237, s75, -v223
	v_exp_f32_e32 v237, v237
	v_add_f32_e32 v193, v236, v193
	v_fma_f32 v238, v238, s75, -v223
	v_exp_f32_e32 v238, v238
	v_add_f32_e32 v194, v237, v194
	v_fma_f32 v239, v239, s75, -v223
	v_exp_f32_e32 v239, v239
	v_add_f32_e32 v193, v238, v193
	v_fma_f32 v240, v240, s75, -v223
	v_exp_f32_e32 v240, v240
	v_add_f32_e32 v194, v239, v194
	v_fma_f32 v241, v241, s75, -v223
	v_exp_f32_e32 v241, v241
	v_add_f32_e32 v193, v240, v193
	v_add_f32_e32 v194, v241, v194
	v_add_f32_e32 v193, v193, v194
	v_cvt_pk_bf16_f32 v242, v226, v227
	v_cvt_pk_bf16_f32 v243, v228, v229
	v_cvt_pk_bf16_f32 v244, v230, v231
	v_cvt_pk_bf16_f32 v245, v232, v233
	v_cvt_pk_bf16_f32 v246, v234, v235
	v_cvt_pk_bf16_f32 v247, v236, v237
	v_cvt_pk_bf16_f32 v248, v238, v239
	v_cvt_pk_bf16_f32 v249, v240, v241
	v_add_f32_e32 v155, v155, v193
	s_nop 1
	v_mfma_f32_32x32x16_bf16 v[34:49], v[142:145], v[242:245], v[34:49]
	v_mfma_f32_32x32x16_bf16 v[2:17], v[134:137], v[242:245], v[2:17]
	v_mfma_f32_32x32x16_bf16 v[34:49], v[138:141], v[246:249], v[34:49]
	v_mfma_f32_32x32x16_bf16 v[2:17], v[130:133], v[246:249], v[2:17]
